# race-free one-barrier diff loop (K ring one tile ahead of V ring) + write-through stores for the W_in projection output
# speedup vs baseline: 1.0269x; 1.0025x over previous
; template <int DV, int NMAP>
; __device__ __forceinline__ void attn_unit(LAS unsigned char* lds, const bf16_t* U, bf16_t* MIX, const float* logf, int b, int h, int qb, float lam, float slope2, const float* gn, float outscale, const int tid) {
;     ...
;     __syncthreads();
;     AT_DMA(0, 0);
;     if (NT > 1) AT_DMA(1, 1);
.LBB0_217:
	s_or_b64 exec, exec, s[30:31]
	s_ashr_i32 s36, s33, 6
	s_and_b32 s61, s36, 3
	s_lshl_b32 s27, s27, 9
	s_lshl_b32 s30, s61, 5
	s_and_b32 s37, s27, 0x3800
	s_or_b32 s62, s30, s62
	v_or_b32_e32 v0, s37, v122
	v_or_b32_e32 v147, s62, v0
	v_mov_b64_e32 v[2:3], s[84:85]
	s_ashr_i32 s60, s33, 8
	v_mad_u64_u32 v[2:3], s[30:31], v147, s87, v[2:3]
	s_lshl_b32 s27, s20, 7
	s_lshl_b32 s20, s20, 8
	s_lshl_b32 s30, s60, 6
	v_lshl_add_u64 v[2:3], v[2:3], 0, s[20:21]
	s_ashr_i32 s31, s30, 31
	v_lshl_add_u64 v[2:3], s[30:31], 1, v[2:3]
	v_lshlrev_b32_e32 v0, 1, v126
	v_lshl_add_u64 v[2:3], v[2:3], 0, v[0:1]
	global_load_dwordx4 v[98:101], v[2:3], off offset:3168
	global_load_dwordx4 v[102:105], v[2:3], off offset:3136
	global_load_dwordx4 v[106:109], v[2:3], off offset:3104
	global_load_dwordx4 v[110:113], v[2:3], off offset:3072
	v_or_b32_e32 v0, s37, v123
	v_mul_u32_u24_e32 v0, 0xc00, v0
	v_lshlrev_b32_e32 v0, 1, v0
	s_lshl_b32 s30, s36, 3
	v_lshl_add_u64 v[2:3], s[84:85], 0, v[0:1]
	s_ashr_i32 s31, s30, 31
	v_lshl_add_u64 v[2:3], v[2:3], 0, s[20:21]
	s_lshl_b64 s[40:41], s[30:31], 1
	s_mul_i32 s65, s36, 0x420
	v_lshl_add_u64 v[4:5], v[2:3], 0, s[40:41]
	v_lshl_or_b32 v2, s61, 4, v127
	s_add_i32 s67, s65, 0
	v_lshl_add_u64 v[6:7], v[4:5], 0, s[22:23]
	v_or_b32_e32 v2, s37, v2
	s_add_i32 s64, s67, 0x2100
	v_mul_u32_u24_e32 v2, 0xc00, v2
	v_lshlrev_b32_e32 v2, 1, v2
	v_mov_b32_e32 v3, v1
	s_lshl_b32 s30, s60, 5
	v_lshl_add_u64 v[8:9], s[84:85], 0, v[2:3]
	s_ashr_i32 s31, s30, 31
	v_lshl_add_u64 v[8:9], v[8:9], 0, s[20:21]
	s_lshr_b32 s63, s63, 6
	v_or_b32_e32 v148, s62, v122
	v_mov_b32_e32 v14, v1
	v_mov_b32_e32 v15, v1
	v_mov_b32_e32 v10, v1
	v_mov_b32_e32 v11, v1
	v_mov_b32_e32 v12, v1
	v_mov_b32_e32 v13, v1
	v_mov_b32_e32 v150, 0
	v_mov_b32_e32 v151, v142
	s_waitcnt vmcnt(0)
	s_waitcnt lgkmcnt(0)
	s_barrier
	s_mov_b32 s41, m0
	s_mov_b32 s68, s36
	s_mov_b32 s65, s60
	s_or_b32 s40, s62, 31
	s_lshr_b32 s40, s40, 6
	s_mov_b32 s37, 0
	v_mov_b64_e32 v[118:119], v[6:7]
	s_lshl_b32 s30, s60, 6
	s_mov_b32 s31, 0
	v_lshl_add_u64 v[138:139], v[8:9], 0, s[30:31]
	v_lshlrev_b32_e32 v116, 1, v128
	v_mov_b32_e32 v117, 0
	v_lshl_add_u64 v[138:139], v[138:139], 0, v[116:117]
	s_mov_b64 s[30:31], 0x1400
	v_lshl_add_u64 v[138:139], v[138:139], 0, s[30:31]
	v_and_b32_e32 v180, 7, v123
	v_sub_u32_e32 v180, v180, v123
	s_lshl_b32 s30, s68, 3
	v_add_u32_e32 v180, s30, v180
	v_mul_i32_i24_e32 v180, 0x1800, v180
	v_lshrrev_b32_e32 v181, 3, v123
	v_subrev_u32_e32 v181, s68, v181
	v_lshl_add_u32 v180, v181, 4, v180
	v_ashrrev_i32_e32 v181, 31, v180
	v_lshl_add_u64 v[136:137], v[118:119], 0, v[180:181]
	v_bfe_u32 v180, v123, 2, 3
	v_lshrrev_b32_e32 v181, 2, v123
	v_sub_u32_e32 v180, v180, v181
	s_and_b32 s31, s68, 3
	s_lshl_b32 s31, s31, 4
	s_lshl_b32 s30, s68, 3
	s_sub_i32 s30, s30, s31
	v_add_u32_e32 v180, s30, v180
	v_mul_i32_i24_e32 v180, 0x1800, v180
	v_lshrrev_b32_e32 v181, 5, v123
	s_lshr_b32 s31, s68, 2
	v_subrev_u32_e32 v181, s31, v181
	v_lshl_add_u32 v180, v181, 6, v180
	v_ashrrev_i32_e32 v181, 31, v180
	v_lshl_add_u64 v[138:139], v[138:139], 0, v[180:181]
	s_lshr_b32 s30, s68, 2
	s_mul_i32 s30, s30, 0x1080
	s_and_b32 s31, s68, 3
	s_lshl_b32 s31, s31, 10
	s_add_i32 s30, s30, s31
	s_bfe_u32 s31, s68, 0x10001
	s_lshl_b32 s31, s31, 7
	s_add_i32 s30, s30, s31
	s_add_i32 s64, s30, 0x2100
	s_mul_i32 s30, s68, 0x800
	s_add_i32 s66, s30, 0x12900
	v_lshrrev_b32_e32 v180, 3, v122
	v_lshlrev_b32_e32 v180, 10, v180
	v_bfe_u32 v181, v122, 4, 1
	v_lshl_add_u32 v180, v181, 7, v180
	v_lshrrev_b32_e32 v181, 5, v123
	v_lshl_add_u32 v180, v181, 7, v180
	v_and_b32_e32 v181, 7, v122
	v_lshl_add_u32 v244, v181, 4, v180
	v_lshl_add_u32 v121, v148, 2, 0
	s_mov_b32 s30, 0
	s_cmp_ge_u32 s30, s63
	s_cbranch_scc1 .Ldf_nkp0
	s_and_b32 s31, s30, 3
	s_mul_i32 s31, s31, 0x4200
	s_add_i32 s31, s31, s64
	s_mov_b32 m0, s31
	v_lshl_add_u64 v[116:117], v[136:137], 0, s[24:25]
	global_load_lds_dwordx4 v[136:137], off
	s_add_i32 m0, s31, 0x2100
	v_lshl_add_u64 v[136:137], v[136:137], 0, s[28:29]
	global_load_lds_dwordx4 v[116:117], off
.Ldf_nkp0:
	s_mov_b32 s30, 0
	s_cmp_ge_u32 s30, s63
	s_cbranch_scc1 .Ldf_nvp1
	s_and_b32 s20, s30, 3
	s_lshl_b32 s20, s20, 14
	s_add_i32 s20, s20, s66
	s_mov_b32 m0, s20
	v_lshl_add_u64 v[116:117], v[138:139], 0, s[24:25]
	global_load_lds_dwordx4 v[138:139], off
	s_add_i32 m0, s20, 0x400
	v_lshl_add_u64 v[138:139], v[138:139], 0, s[28:29]
	global_load_lds_dwordx4 v[116:117], off
.Ldf_nvp1:
	s_add_i32 s30, s30, 1
	s_cmp_ge_u32 s30, s63
	s_cbranch_scc1 .Ldf_nkp1
	s_and_b32 s31, s30, 3
	s_mul_i32 s31, s31, 0x4200
	s_add_i32 s31, s31, s64
	s_mov_b32 m0, s31
	v_lshl_add_u64 v[116:117], v[136:137], 0, s[24:25]
	global_load_lds_dwordx4 v[136:137], off
	s_add_i32 m0, s31, 0x2100
	v_lshl_add_u64 v[136:137], v[136:137], 0, s[28:29]
	global_load_lds_dwordx4 v[116:117], off
.Ldf_nkp1:
	s_mov_b32 s30, 1
	s_cmp_ge_u32 s30, s63
	s_cbranch_scc1 .Ldf_nvp2
	s_and_b32 s20, s30, 3
	s_lshl_b32 s20, s20, 14
	s_add_i32 s20, s20, s66
	s_mov_b32 m0, s20
	v_lshl_add_u64 v[116:117], v[138:139], 0, s[24:25]
	global_load_lds_dwordx4 v[138:139], off
	s_add_i32 m0, s20, 0x400
	v_lshl_add_u64 v[138:139], v[138:139], 0, s[28:29]
	global_load_lds_dwordx4 v[116:117], off

; template <int DV, int NMAP>
; __device__ __forceinline__ void attn_unit(LAS unsigned char* lds, const bf16_t* U, bf16_t* MIX, const float* logf, int b, int h, int qb, float lam, float slope2, const float* gn, float outscale, const int tid) {
;     ...
;     const float m_run = bias[qrow0 + r32];
;     float l_run = 0.f;
;     f32x16 o[NDB];
; #pragma unroll
;     for (int d = 0; d < NDB; ++d)
; #pragma unroll
;         for (int r = 0; r < 16; ++r) o[d][r] = 0.f;
;     const int vofs = (4 * hi + ((lane & 15) >> 2)) * 64 + ((lane >> 4) & 1) * 32 + (lane & 3) * 8;
;     int st = 0, st2 = 2;
;     for (int t = 0; t < NT; ++t) {
;         if (t + 1 < NT) { if (PER == 2) asm volatile("s_waitcnt vmcnt(2)\n\ts_barrier" ::: "memory"); else asm volatile("s_waitcnt vmcnt(4)\n\ts_barrier" ::: "memory"); }
.Ldf_nkp2:
	ds_read_b32 v149, v121
	v_mov_b32_e32 v2, 0
	v_mov_b32_e32 v3, 0
	v_mov_b32_e32 v4, 0
	v_mov_b32_e32 v5, 0
	v_mov_b32_e32 v6, 0
	v_mov_b32_e32 v7, 0
	v_mov_b32_e32 v8, 0
	v_mov_b32_e32 v9, 0
	v_mov_b32_e32 v10, 0
	v_mov_b32_e32 v11, 0
	v_mov_b32_e32 v12, 0
	v_mov_b32_e32 v13, 0
	v_mov_b32_e32 v14, 0
	v_mov_b32_e32 v15, 0
	v_mov_b32_e32 v16, 0
	v_mov_b32_e32 v17, 0
	v_mov_b32_e32 v18, 0
	v_mov_b32_e32 v19, 0
	v_mov_b32_e32 v20, 0
	v_mov_b32_e32 v21, 0
	v_mov_b32_e32 v22, 0
	v_mov_b32_e32 v23, 0
	v_mov_b32_e32 v24, 0
	v_mov_b32_e32 v25, 0
	v_mov_b32_e32 v26, 0
	v_mov_b32_e32 v27, 0
	v_mov_b32_e32 v28, 0
	v_mov_b32_e32 v29, 0
	v_mov_b32_e32 v30, 0
	v_mov_b32_e32 v31, 0
	v_mov_b32_e32 v32, 0
	v_mov_b32_e32 v33, 0
	v_mov_b32_e32 v34, 0
	v_mov_b32_e32 v35, 0
	v_mov_b32_e32 v36, 0
	v_mov_b32_e32 v37, 0
	v_mov_b32_e32 v38, 0
	v_mov_b32_e32 v39, 0
	v_mov_b32_e32 v40, 0
	v_mov_b32_e32 v41, 0
	v_mov_b32_e32 v42, 0
	v_mov_b32_e32 v43, 0
	v_mov_b32_e32 v44, 0
	v_mov_b32_e32 v45, 0
	v_mov_b32_e32 v46, 0
	v_mov_b32_e32 v47, 0
	v_mov_b32_e32 v48, 0
	v_mov_b32_e32 v49, 0
	v_mov_b32_e32 v50, 0
	v_mov_b32_e32 v51, 0
	v_mov_b32_e32 v52, 0
	v_mov_b32_e32 v53, 0
	v_mov_b32_e32 v54, 0
	v_mov_b32_e32 v55, 0
	v_mov_b32_e32 v56, 0
	v_mov_b32_e32 v57, 0
	v_mov_b32_e32 v58, 0
	v_mov_b32_e32 v59, 0
	v_mov_b32_e32 v60, 0
	v_mov_b32_e32 v61, 0
	v_mov_b32_e32 v62, 0
	v_mov_b32_e32 v63, 0
	v_mov_b32_e32 v64, 0
	v_mov_b32_e32 v65, 0
	s_cmp_gt_u32 s63, 2
	s_cbranch_scc1 .Ldf_w0
	s_waitcnt vmcnt(2)
	s_branch .Ldf_w0d

; template <int DV, int NMAP>
; __device__ __forceinline__ void attn_unit(LAS unsigned char* lds, const bf16_t* U, bf16_t* MIX, const float* logf, int b, int h, int qb, float lam, float slope2, const float* gn, float outscale, const int tid) {
;     ...
;     for (int t = 0; t < NT; ++t) {
;         if (t + 1 < NT) { if (PER == 2) asm volatile("s_waitcnt vmcnt(2)\n\ts_barrier" ::: "memory"); else asm volatile("s_waitcnt vmcnt(4)\n\ts_barrier" ::: "memory"); }
;         else asm volatile("s_waitcnt vmcnt(0)\n\ts_barrier" ::: "memory");
;         if (t + 2 < NT) AT_DMA(t + 2, st2);
.Ldf_w0d:
	s_barrier
	s_cmp_eq_u32 s65, 0
	s_cbranch_scc1 .Ldf_P
	s_barrier
	s_mov_b32 s30, 2
	s_cmp_ge_u32 s30, s63
	s_cbranch_scc1 .Ldf_nvpp
	s_and_b32 s20, s30, 3
	s_lshl_b32 s20, s20, 14
	s_add_i32 s20, s20, s66
	s_mov_b32 m0, s20
	v_lshl_add_u64 v[116:117], v[138:139], 0, s[24:25]
	global_load_lds_dwordx4 v[138:139], off
	s_add_i32 m0, s20, 0x400
	v_lshl_add_u64 v[138:139], v[138:139], 0, s[28:29]
	global_load_lds_dwordx4 v[116:117], off

; #define LAS __attribute__((address_space(3)))
; template <int DV, int NMAP>
; __device__ __forceinline__ void attn_unit(LAS unsigned char* lds, const bf16_t* U, bf16_t* MIX, const float* logf, int b, int h, int qb, float lam, float slope2, const float* gn, float outscale, const int tid) {
;     ...
;         if (64 * t <= qrow0 + 31) {
;             const LAS unsigned char* Kb = lds + AT_K + (st * NMAP + map) * AT_KT + r32 * 16;
;             const LAS unsigned char* Vb = lds + AT_V + st * VT + vofs;
;             f32x16 p0, p1;
;             {
;                 const LAS float* bp = bias + 64 * t + 4 * hi;
; #pragma unroll
;                 for (int g = 0; g < 4; ++g) { const f32x4 v = *(const LAS f32x4*)(bp + 8 * g), w = *(const LAS f32x4*)(bp + 32 + 8 * g);
;                     p0[4 * g] = v[0]; p0[4 * g + 1] = v[1]; p0[4 * g + 2] = v[2]; p0[4 * g + 3] = v[3]; p1[4 * g] = w[0]; p1[4 * g + 1] = w[1]; p1[4 * g + 2] = w[2]; p1[4 * g + 3] = w[3]; }
;             }
;             {
;                 bf16x8 kf[8];
; #pragma unroll
;                 for (int d0 = 0; d0 < 4; ++d0) { kf[2 * d0] = *(const LAS bf16x8*)(Kb + (2 * d0 + hi) * 1056); kf[2 * d0 + 1] = *(const LAS bf16x8*)(Kb + (2 * d0 + hi) * 1056 + 512); }
;                 __builtin_amdgcn_sched_barrier(0);
; #pragma unroll
;                 for (int d0 = 0; d0 < 4; ++d0) {
;                     p0 = __builtin_amdgcn_mfma_f32_32x32x16_bf16(kf[2 * d0], qr[d0], p0, 0, 0, 0);
;                     p1 = __builtin_amdgcn_mfma_f32_32x32x16_bf16(kf[2 * d0 + 1], qr[d0], p1, 0, 0, 0);
;                 }
;                 __builtin_amdgcn_sched_barrier(0);
;             }
;             if (64 * t + 63 > qrow0) {
;                 const int q = qrow0 + r32, kv0 = 64 * t + 4 * hi;
; #pragma unroll
;                 for (int r = 0; r < 16; ++r) { const int kv = kv0 + (r & 3) + 8 * (r >> 2); if (kv > q) p0[r] = -1e30f; if (kv + 32 > q) p1[r] = -1e30f; }
;             }
.Ldf_nkpp:
.Ldf_P:
	ds_read_b128 v[82:85], v151
	ds_read_b128 v[86:89], v151 offset:32
	ds_read_b128 v[90:93], v151 offset:64
	ds_read_b128 v[94:97], v151 offset:96
	ds_read_b128 v[66:69], v151 offset:128
	ds_read_b128 v[70:73], v151 offset:160
	ds_read_b128 v[74:77], v151 offset:192
	ds_read_b128 v[78:81], v151 offset:224
	s_mov_b32 s30, 0
	s_and_b32 s30, s30, 3
	s_lshl_b32 s30, s30, 1
	s_add_i32 s30, s30, s60
	s_mulk_i32 s30, 0x2100
	v_add_u32_e32 v118, s30, v244
	ds_read_b128 v[168:171], v118 offset:8448
	ds_read_b128 v[172:175], v118 offset:12672
	ds_read_b128 v[176:179], v118 offset:8704
	ds_read_b128 v[190:193], v118 offset:12928
	ds_read_b128 v[194:197], v118 offset:8960
	ds_read_b128 v[198:201], v118 offset:13184
	ds_read_b128 v[234:237], v118 offset:9216
	ds_read_b128 v[238:241], v118 offset:13440
	s_waitcnt lgkmcnt(6)
	v_mfma_f32_32x32x16_bf16 v[82:97], v[168:171], v[110:113], v[82:97]
	v_mfma_f32_32x32x16_bf16 v[66:81], v[172:175], v[110:113], v[66:81]
	s_waitcnt lgkmcnt(4)
	v_mfma_f32_32x32x16_bf16 v[82:97], v[176:179], v[106:109], v[82:97]
	v_mfma_f32_32x32x16_bf16 v[66:81], v[190:193], v[106:109], v[66:81]
	s_waitcnt lgkmcnt(2)
	v_mfma_f32_32x32x16_bf16 v[82:97], v[194:197], v[102:105], v[82:97]
	v_mfma_f32_32x32x16_bf16 v[66:81], v[198:201], v[102:105], v[66:81]
	s_waitcnt lgkmcnt(0)
	v_mfma_f32_32x32x16_bf16 v[82:97], v[234:237], v[98:101], v[82:97]
	v_mfma_f32_32x32x16_bf16 v[66:81], v[238:241], v[98:101], v[66:81]
	s_movk_i32 s36, 63
	s_cmp_le_u32 s36, s62
	s_cbranch_scc1 .Ldf_P_nomask
	v_add_u32_e32 v0, s36, v130
	v_subrev_u32_e32 v115, 31, v0
	v_subrev_u32_e32 v114, 63, v0
	v_cmp_le_u32_e32 vcc, v115, v148
	s_nop 5
	v_cndmask_b32_e32 v66, v230, v66, vcc
	v_cmp_lt_u32_e32 vcc, v114, v148
	s_nop 1
	v_cndmask_b32_e32 v83, v230, v83, vcc
	v_cmp_le_u32_e32 vcc, v114, v148
	v_subrev_u32_e32 v114, 30, v0
	s_nop 0
	v_cndmask_b32_e32 v82, v230, v82, vcc
	v_cmp_le_u32_e32 vcc, v114, v148
	v_subrev_u32_e32 v114, 61, v0
	s_nop 0
	v_cndmask_b32_e32 v67, v230, v67, vcc
	v_cmp_le_u32_e32 vcc, v114, v148
	v_subrev_u32_e32 v114, 29, v0
	s_nop 0
	v_cndmask_b32_e32 v84, v230, v84, vcc
	v_cmp_le_u32_e32 vcc, v114, v148
	v_subrev_u32_e32 v114, 60, v0
	s_nop 0
	v_cndmask_b32_e32 v68, v230, v68, vcc
	v_cmp_le_u32_e32 vcc, v114, v148
	v_subrev_u32_e32 v114, 28, v0
	s_nop 0
	v_cndmask_b32_e32 v85, v230, v85, vcc
	v_cmp_le_u32_e32 vcc, v114, v148
	v_subrev_u32_e32 v114, 55, v0
	s_nop 0
	v_cndmask_b32_e32 v69, v230, v69, vcc
	v_cmp_le_u32_e32 vcc, v114, v148
	v_subrev_u32_e32 v114, 23, v0
	s_nop 0
	v_cndmask_b32_e32 v86, v230, v86, vcc
	v_cmp_le_u32_e32 vcc, v114, v148
	v_subrev_u32_e32 v114, 54, v0
	s_nop 0
	v_cndmask_b32_e32 v70, v230, v70, vcc
	v_cmp_le_u32_e32 vcc, v114, v148
	v_subrev_u32_e32 v114, 22, v0
	s_nop 0
	v_cndmask_b32_e32 v87, v230, v87, vcc
	v_cmp_le_u32_e32 vcc, v114, v148
	v_subrev_u32_e32 v114, 53, v0
	s_nop 0
	v_cndmask_b32_e32 v71, v230, v71, vcc
	v_cmp_le_u32_e32 vcc, v114, v148
	v_subrev_u32_e32 v114, 21, v0
	s_nop 0
	v_cndmask_b32_e32 v88, v230, v88, vcc
	v_cmp_le_u32_e32 vcc, v114, v148
	v_subrev_u32_e32 v114, 52, v0
	s_nop 0
	v_cndmask_b32_e32 v72, v230, v72, vcc
	v_cmp_le_u32_e32 vcc, v114, v148
	v_subrev_u32_e32 v114, 20, v0
	s_nop 0
	v_cndmask_b32_e32 v89, v230, v89, vcc
	v_cmp_le_u32_e32 vcc, v114, v148
	v_subrev_u32_e32 v114, 47, v0
	s_nop 0
	v_cndmask_b32_e32 v73, v230, v73, vcc
	v_cmp_le_u32_e32 vcc, v114, v148
	v_add_u32_e32 v114, -15, v0
	s_nop 0
	v_cndmask_b32_e32 v90, v230, v90, vcc
	v_cmp_le_u32_e32 vcc, v114, v148
	v_subrev_u32_e32 v114, 46, v0
	s_nop 0
	v_cndmask_b32_e32 v74, v230, v74, vcc
	v_cmp_le_u32_e32 vcc, v114, v148
	v_add_u32_e32 v114, -14, v0
	s_nop 0
	v_cndmask_b32_e32 v91, v230, v91, vcc
	v_cmp_le_u32_e32 vcc, v114, v148
	v_subrev_u32_e32 v114, 45, v0
	s_nop 0
	v_cndmask_b32_e32 v75, v230, v75, vcc
	v_cmp_le_u32_e32 vcc, v114, v148
	v_add_u32_e32 v114, -13, v0
	s_nop 0
	v_cndmask_b32_e32 v92, v230, v92, vcc
	v_cmp_le_u32_e32 vcc, v114, v148
	v_subrev_u32_e32 v114, 44, v0
	s_nop 0
	v_cndmask_b32_e32 v76, v230, v76, vcc
	v_cmp_le_u32_e32 vcc, v114, v148
	v_add_u32_e32 v114, -12, v0
	s_nop 0
	v_cndmask_b32_e32 v93, v230, v93, vcc
	v_cmp_le_u32_e32 vcc, v114, v148
	v_subrev_u32_e32 v114, 39, v0
	s_nop 0
	v_cndmask_b32_e32 v77, v230, v77, vcc
	v_cmp_le_u32_e32 vcc, v114, v148
	v_add_u32_e32 v114, -7, v0
	s_nop 0
	v_cndmask_b32_e32 v94, v230, v94, vcc
	v_cmp_le_u32_e32 vcc, v114, v148
	v_subrev_u32_e32 v114, 38, v0
	s_nop 0
	v_cndmask_b32_e32 v78, v230, v78, vcc
	v_cmp_le_u32_e32 vcc, v114, v148
	v_add_u32_e32 v114, -6, v0
	s_nop 0
	v_cndmask_b32_e32 v95, v230, v95, vcc
	v_cmp_le_u32_e32 vcc, v114, v148
	v_subrev_u32_e32 v114, 37, v0
	s_nop 0
	v_cndmask_b32_e32 v79, v230, v79, vcc
	v_cmp_le_u32_e32 vcc, v114, v148
	v_add_u32_e32 v114, -5, v0
	s_nop 0
	v_cndmask_b32_e32 v96, v230, v96, vcc
	v_cmp_le_u32_e32 vcc, v114, v148
	v_subrev_u32_e32 v114, 36, v0
	v_add_u32_e32 v0, -4, v0
	v_cndmask_b32_e32 v80, v230, v80, vcc
	v_cmp_le_u32_e32 vcc, v114, v148
	s_nop 1
	v_cndmask_b32_e32 v97, v230, v97, vcc
	v_cmp_le_u32_e32 vcc, v0, v148
	s_nop 1
	v_cndmask_b32_e32 v81, v230, v81, vcc
.Ldf_P_nomask:
	s_cmp_lg_u32 s65, 0
	s_cbranch_scc1 .Ldf_loop
	s_barrier

; __device__ __forceinline__ unsigned pk_bf16(float lo, float hi) { return pg8::cvt_pk_bf16(lo, hi); }
; __device__ __forceinline__ s16x4 vtr(const LAS unsigned char* p) { typedef short v4i16_t __attribute__((ext_vector_type(4))); return __builtin_bit_cast(s16x4, __builtin_amdgcn_ds_read_tr16_b64_v4i16((LAS v4i16_t*)p)); }
; template <int DV, int NMAP>
; __device__ __forceinline__ void attn_unit(LAS unsigned char* lds, const bf16_t* U, bf16_t* MIX, const float* logf, int b, int h, int qb, float lam, float slope2, const float* gn, float outscale, const int tid) {
;     ...
;             s16x4 lo[2][4], hh[2][4];
; #pragma unroll
;             for (int e = 0; e < 2; ++e)
; #pragma unroll
;                 for (int s = 0; s < 4; ++s) { lo[e][s] = vtr(Vb + e * 4096 + s * 1024); hh[e][s] = vtr(Vb + e * 4096 + s * 1024 + 512); }
;             __builtin_amdgcn_sched_barrier(0);
;             {
;                 float s0 = 0.f, s1 = 0.f, s2 = 0.f, s3 = 0.f;
; #pragma unroll
;                 for (int r = 0; r < 16; r += 2) { p0[r] = __builtin_amdgcn_exp2f(p0[r] - m_run); p0[r + 1] = __builtin_amdgcn_exp2f(p0[r + 1] - m_run); p1[r] = __builtin_amdgcn_exp2f(p1[r] - m_run); p1[r + 1] = __builtin_amdgcn_exp2f(p1[r + 1] - m_run);
;                     s0 += p0[r]; s1 += p0[r + 1]; s2 += p1[r]; s3 += p1[r + 1]; }
;                 l_run += (s0 + s1) + (s2 + s3);
;             }
;             bf16x8 pk[4];
;             {
;                 u32x4 w;
;                 w.x = pk_bf16(p0[0], p0[1]); w.y = pk_bf16(p0[2], p0[3]); w.z = pk_bf16(p0[4], p0[5]); w.w = pk_bf16(p0[6], p0[7]); pk[0] = __builtin_bit_cast(bf16x8, w);
;                 w.x = pk_bf16(p0[8], p0[9]); w.y = pk_bf16(p0[10], p0[11]); w.z = pk_bf16(p0[12], p0[13]); w.w = pk_bf16(p0[14], p0[15]); pk[1] = __builtin_bit_cast(bf16x8, w);
;                 w.x = pk_bf16(p1[0], p1[1]); w.y = pk_bf16(p1[2], p1[3]); w.z = pk_bf16(p1[4], p1[5]); w.w = pk_bf16(p1[6], p1[7]); pk[2] = __builtin_bit_cast(bf16x8, w);
;                 w.x = pk_bf16(p1[8], p1[9]); w.y = pk_bf16(p1[10], p1[11]); w.z = pk_bf16(p1[12], p1[13]); w.w = pk_bf16(p1[14], p1[15]); pk[3] = __builtin_bit_cast(bf16x8, w);
;             }
.Ldf_A_skip:
	s_cmp_eq_u32 s65, 0
	s_cbranch_scc1 .Ldf_a_done
	s_add_i32 s30, s37, 3
	s_cmp_lt_u32 s30, s63
	s_cbranch_scc1 .Ldf_a_w4
	s_cmp_eq_u32 s30, s63
	s_cbranch_scc1 .Ldf_a_w2
	s_waitcnt vmcnt(0)
	s_branch .Ldf_a_done
.Ldf_a_w2:
	s_waitcnt vmcnt(2)
	s_branch .Ldf_a_done

; template <int DV, int NMAP>
; __device__ __forceinline__ void attn_unit(LAS unsigned char* lds, const bf16_t* U, bf16_t* MIX, const float* logf, int b, int h, int qb, float lam, float slope2, const float* gn, float outscale, const int tid) {
;     ...
;         if (t + 1 < NT) { if (PER == 2) asm volatile("s_waitcnt vmcnt(2)\n\ts_barrier" ::: "memory"); else asm volatile("s_waitcnt vmcnt(4)\n\ts_barrier" ::: "memory"); }
;         else asm volatile("s_waitcnt vmcnt(0)\n\ts_barrier" ::: "memory");
;         if (t + 2 < NT) AT_DMA(t + 2, st2);
.Ldf_a_done:
	s_cmp_eq_u32 s65, 0
	s_cbranch_scc1 .Ldf_nobarA
	s_barrier
.Ldf_nobarA:
	s_add_i32 s30, s37, 2
	s_add_i32 s30, s30, s65
	s_cmp_ge_u32 s30, s63
	s_cbranch_scc1 .Ldf_nvb
	s_and_b32 s20, s30, 3
	s_lshl_b32 s20, s20, 14
	s_add_i32 s20, s20, s66
	s_mov_b32 m0, s20
	v_lshl_add_u64 v[116:117], v[138:139], 0, s[24:25]
	global_load_lds_dwordx4 v[138:139], off
	s_add_i32 m0, s20, 0x400
	v_lshl_add_u64 v[138:139], v[138:139], 0, s[28:29]
	global_load_lds_dwordx4 v[116:117], off

; template <int DV, int NMAP>
; __device__ __forceinline__ void attn_unit(LAS unsigned char* lds, const bf16_t* U, bf16_t* MIX, const float* logf, int b, int h, int qb, float lam, float slope2, const float* gn, float outscale, const int tid) {
;     ...
;     for (int t = 0; t < NT; ++t) {
;         if (t + 1 < NT) { if (PER == 2) asm volatile("s_waitcnt vmcnt(2)\n\ts_barrier" ::: "memory"); else asm volatile("s_waitcnt vmcnt(4)\n\ts_barrier" ::: "memory"); }
;         else asm volatile("s_waitcnt vmcnt(0)\n\ts_barrier" ::: "memory");
;         if (t + 2 < NT) AT_DMA(t + 2, st2);
.Ldf_B_end:
	s_cmp_lg_u32 s65, 0
	s_cbranch_scc1 .Ldf_b_done
	s_add_i32 s30, s37, 3
	s_cmp_lt_u32 s30, s63
	s_cbranch_scc1 .Ldf_b_w4
	s_cmp_eq_u32 s30, s63
	s_cbranch_scc1 .Ldf_b_w2
	s_waitcnt vmcnt(0)
	s_branch .Ldf_b_done

; __device__ __forceinline__ unsigned cvt_pk_bf16(float lo, float hi) { unsigned r; asm volatile("v_cvt_pk_bf16_f32 %0, %1, %2" : "=v"(r) : "v"(lo), "v"(hi)); return r; }
;     __device__ __forceinline__ void operator()(const f32x4 (&acc)[2][2][4][2], const Unit& u, int wr, int wc, int fr, int fq) const {
;     ...
; #pragma unroll
;         for (int ai = 0; ai < 2; ++ai)
; #pragma unroll
;             for (int m = 0; m < 4; ++m) {
;                 const int row = row0 + ai * HALF + m * 16;
;                 const float r = __builtin_amdgcn_rsqf(rr[ai][m] * (1.0f / 1024.0f) + 1e-6f);
;                 f32x4 v[2][2];
; #pragma unroll
;                 for (int bj = 0; bj < 2; ++bj)
; #pragma unroll
;                     for (int n = 0; n < 2; ++n) v[bj][n] = acc[ai][bj][m][n] * r + bv[bj][n];
;                 float sc = 1.f;
;                 if (donorm) {
;                     float ss = 0.f;
; #pragma unroll
;                     for (int bj = 0; bj < 2; ++bj)
; #pragma unroll
;                         for (int n = 0; n < 2; ++n) { const f32x4 t = v[bj][n]; ss += (t[0] * t[0] + t[1] * t[1]) + (t[2] * t[2] + t[3] * t[3]); }
;                     ss += __shfl_xor(ss, 16); ss += __shfl_xor(ss, 32);
;                     sc = 1.0f / sqrtf(ss * (1.0f / 64.0f) + 1e-6f);
;                 }
;                 bf16_t* rowp = U + (size_t)row * 3072 + col0;
; #pragma unroll
;                 for (int bj = 0; bj < 2; ++bj) {
;                     const f32x4 v0 = v[bj][0] * gv[bj][0] * sc, v1 = v[bj][1] * gv[bj][1] * sc;
;                     u32x4 w; w.x = cvt_pk_bf16(v0[0], v0[1]); w.y = cvt_pk_bf16(v0[2], v0[3]); w.z = cvt_pk_bf16(v1[0], v1[1]); w.w = cvt_pk_bf16(v1[2], v1[3]);
;                     *(u32x4*)(rowp + 32 * bj) = w;
;                 }
.LBB0_434:
	v_lshl_or_b32 v138, s66, 8, v233
	v_lshl_add_u32 v177, s67, 8, v187
	v_mov_b64_e32 v[236:237], s[84:85]
	v_pk_mul_f32 v[156:157], v[202:203], v[156:157]
	v_pk_mul_f32 v[148:149], v[206:207], v[148:149]
	v_ashrrev_i32_e32 v139, 31, v138
	v_mad_i64_i32 v[236:237], s[2:3], v177, s87, v[236:237]
	v_pk_mul_f32 v[174:175], v[204:205], v[174:175]
	v_pk_mul_f32 v[156:157], v[156:157], v[176:177] op_sel_hi:[1,0]
	v_pk_mul_f32 v[154:155], v[208:209], v[154:155]
	v_pk_mul_f32 v[148:149], v[148:149], v[176:177] op_sel_hi:[1,0]
	v_pk_mul_f32 v[142:143], v[216:217], v[142:143]
	v_pk_mul_f32 v[140:141], v[214:215], v[140:141]
	v_lshl_add_u64 v[236:237], v[138:139], 1, v[236:237]
	v_pk_mul_f32 v[174:175], v[174:175], v[176:177] op_sel_hi:[1,0]
	v_pk_mul_f32 v[238:239], v[154:155], v[176:177] op_sel_hi:[1,0]
	v_cvt_pk_bf16_f32 v154, v156, v157
	v_cvt_pk_bf16_f32 v155, v174, v175
	v_cvt_pk_bf16_f32 v156, v148, v149
	v_pk_mul_f32 v[146:147], v[212:213], v[146:147]
	v_pk_mul_f32 v[144:145], v[210:211], v[144:145]
	v_pk_mul_f32 v[148:149], v[142:143], v[176:177] op_sel_hi:[1,0]
	v_pk_mul_f32 v[142:143], v[140:141], v[176:177] op_sel_hi:[1,0]
	s_cmp_lt_i32 s11, 5
	v_cvt_pk_bf16_f32 v157, v238, v239
	global_store_dwordx4 v[236:237], v[154:157], off sc1
	v_pk_mul_f32 v[146:147], v[146:147], v[176:177] op_sel_hi:[1,0]
	v_pk_mul_f32 v[144:145], v[144:145], v[176:177] op_sel_hi:[1,0]
	s_nop 0
	v_cvt_pk_bf16_f32 v140, v144, v145
	v_cvt_pk_bf16_f32 v141, v146, v147
	v_cvt_pk_bf16_f32 v142, v142, v143
	v_cvt_pk_bf16_f32 v143, v148, v149
	global_store_dwordx4 v[236:237], v[140:143], off offset:64 sc1
	s_cbranch_scc1 .LBB0_436
	s_cmp_lg_u32 s11, 5
	s_cselect_b64 s[2:3], -1, 0
	s_cbranch_execz .LBB0_437
	s_branch .LBB0_438

; __device__ __forceinline__ unsigned cvt_pk_bf16(float lo, float hi) { unsigned r; asm volatile("v_cvt_pk_bf16_f32 %0, %1, %2" : "=v"(r) : "v"(lo), "v"(hi)); return r; }
;     __device__ __forceinline__ void operator()(const f32x4 (&acc)[2][2][4][2], const Unit& u, int wr, int wc, int fr, int fq) const {
;     ...
; #pragma unroll
;         for (int ai = 0; ai < 2; ++ai)
; #pragma unroll
;             for (int m = 0; m < 4; ++m) {
;                 const int row = row0 + ai * HALF + m * 16;
;                 const float r = __builtin_amdgcn_rsqf(rr[ai][m] * (1.0f / 1024.0f) + 1e-6f);
;                 f32x4 v[2][2];
; #pragma unroll
;                 for (int bj = 0; bj < 2; ++bj)
; #pragma unroll
;                     for (int n = 0; n < 2; ++n) v[bj][n] = acc[ai][bj][m][n] * r + bv[bj][n];
;                 float sc = 1.f;
;                 if (donorm) {
;                     float ss = 0.f;
; #pragma unroll
;                     for (int bj = 0; bj < 2; ++bj)
; #pragma unroll
;                         for (int n = 0; n < 2; ++n) { const f32x4 t = v[bj][n]; ss += (t[0] * t[0] + t[1] * t[1]) + (t[2] * t[2] + t[3] * t[3]); }
;                     ss += __shfl_xor(ss, 16); ss += __shfl_xor(ss, 32);
;                     sc = 1.0f / sqrtf(ss * (1.0f / 64.0f) + 1e-6f);
;                 }
;                 bf16_t* rowp = U + (size_t)row * 3072 + col0;
; #pragma unroll
;                 for (int bj = 0; bj < 2; ++bj) {
;                     const f32x4 v0 = v[bj][0] * gv[bj][0] * sc, v1 = v[bj][1] * gv[bj][1] * sc;
;                     u32x4 w; w.x = cvt_pk_bf16(v0[0], v0[1]); w.y = cvt_pk_bf16(v0[2], v0[3]); w.z = cvt_pk_bf16(v1[0], v1[1]); w.w = cvt_pk_bf16(v1[2], v1[3]);
;                     *(u32x4*)(rowp + 32 * bj) = w;
;                 }
.LBB0_440:
	v_or_b32_e32 v141, 16, v177
	v_mov_b64_e32 v[142:143], s[84:85]
	v_mad_i64_i32 v[142:143], s[2:3], v141, s87, v[142:143]
	v_pk_mul_f32 v[132:133], v[204:205], v[132:133]
	v_pk_mul_f32 v[130:131], v[202:203], v[130:131]
	v_pk_mul_f32 v[128:129], v[208:209], v[128:129]
	v_pk_mul_f32 v[126:127], v[206:207], v[126:127]
	v_lshl_add_u64 v[142:143], v[138:139], 1, v[142:143]
	v_pk_mul_f32 v[132:133], v[132:133], v[140:141] op_sel_hi:[1,0]
	v_pk_mul_f32 v[130:131], v[130:131], v[140:141] op_sel_hi:[1,0]
	v_pk_mul_f32 v[144:145], v[128:129], v[140:141] op_sel_hi:[1,0]
	v_pk_mul_f32 v[128:129], v[126:127], v[140:141] op_sel_hi:[1,0]
	v_cvt_pk_bf16_f32 v126, v130, v131
	v_cvt_pk_bf16_f32 v127, v132, v133
	v_pk_mul_f32 v[120:121], v[216:217], v[120:121]
	v_pk_mul_f32 v[118:119], v[214:215], v[118:119]
	v_cvt_pk_bf16_f32 v128, v128, v129
	v_cvt_pk_bf16_f32 v129, v144, v145
	global_store_dwordx4 v[142:143], v[126:129], off sc1
	v_pk_mul_f32 v[124:125], v[212:213], v[124:125]
	v_pk_mul_f32 v[122:123], v[210:211], v[122:123]
	v_pk_mul_f32 v[126:127], v[120:121], v[140:141] op_sel_hi:[1,0]
	v_pk_mul_f32 v[120:121], v[118:119], v[140:141] op_sel_hi:[1,0]
	s_cmp_lt_i32 s11, 5
	v_pk_mul_f32 v[124:125], v[124:125], v[140:141] op_sel_hi:[1,0]
	v_pk_mul_f32 v[122:123], v[122:123], v[140:141] op_sel_hi:[1,0]
	s_nop 0
	v_cvt_pk_bf16_f32 v118, v122, v123
	v_cvt_pk_bf16_f32 v119, v124, v125
	v_cvt_pk_bf16_f32 v120, v120, v121
	v_cvt_pk_bf16_f32 v121, v126, v127
	global_store_dwordx4 v[142:143], v[118:121], off offset:64 sc1
	s_cbranch_scc1 .LBB0_442
	s_cmp_lg_u32 s11, 5
	s_cselect_b64 s[2:3], -1, 0
	s_cbranch_execz .LBB0_443
	s_branch .LBB0_444

; __device__ __forceinline__ unsigned cvt_pk_bf16(float lo, float hi) { unsigned r; asm volatile("v_cvt_pk_bf16_f32 %0, %1, %2" : "=v"(r) : "v"(lo), "v"(hi)); return r; }
;     __device__ __forceinline__ void operator()(const f32x4 (&acc)[2][2][4][2], const Unit& u, int wr, int wc, int fr, int fq) const {
;     ...
;                 bf16_t* rowp = U + (size_t)row * 3072 + col0;
; #pragma unroll
;                 for (int bj = 0; bj < 2; ++bj) {
;                     const f32x4 v0 = v[bj][0] * gv[bj][0] * sc, v1 = v[bj][1] * gv[bj][1] * sc;
;                     u32x4 w; w.x = cvt_pk_bf16(v0[0], v0[1]); w.y = cvt_pk_bf16(v0[2], v0[3]); w.z = cvt_pk_bf16(v1[0], v1[1]); w.w = cvt_pk_bf16(v1[2], v1[3]);
;                     *(u32x4*)(rowp + 32 * bj) = w;
.LBB0_446:
	v_or_b32_e32 v119, 32, v177
	v_mov_b64_e32 v[120:121], s[84:85]
	v_mad_i64_i32 v[120:121], s[2:3], v119, s87, v[120:121]
	v_pk_mul_f32 v[108:109], v[204:205], v[108:109]
	v_pk_mul_f32 v[106:107], v[202:203], v[106:107]
	v_pk_mul_f32 v[104:105], v[208:209], v[104:105]
	v_pk_mul_f32 v[102:103], v[206:207], v[102:103]
	v_lshl_add_u64 v[120:121], v[138:139], 1, v[120:121]
	v_pk_mul_f32 v[108:109], v[108:109], v[118:119] op_sel_hi:[1,0]
	v_pk_mul_f32 v[106:107], v[106:107], v[118:119] op_sel_hi:[1,0]
	v_pk_mul_f32 v[122:123], v[104:105], v[118:119] op_sel_hi:[1,0]
	v_pk_mul_f32 v[104:105], v[102:103], v[118:119] op_sel_hi:[1,0]
	v_cvt_pk_bf16_f32 v102, v106, v107
	v_cvt_pk_bf16_f32 v103, v108, v109
	v_pk_mul_f32 v[92:93], v[216:217], v[92:93]
	v_pk_mul_f32 v[90:91], v[214:215], v[90:91]
	v_cvt_pk_bf16_f32 v104, v104, v105
	v_cvt_pk_bf16_f32 v105, v122, v123
	global_store_dwordx4 v[120:121], v[102:105], off sc1
	v_pk_mul_f32 v[100:101], v[212:213], v[100:101]
	v_pk_mul_f32 v[98:99], v[210:211], v[98:99]
	v_pk_mul_f32 v[102:103], v[92:93], v[118:119] op_sel_hi:[1,0]
	v_pk_mul_f32 v[92:93], v[90:91], v[118:119] op_sel_hi:[1,0]
	s_cmp_lt_i32 s11, 5
	v_pk_mul_f32 v[100:101], v[100:101], v[118:119] op_sel_hi:[1,0]
	v_pk_mul_f32 v[98:99], v[98:99], v[118:119] op_sel_hi:[1,0]
	s_nop 0
	v_cvt_pk_bf16_f32 v90, v98, v99
	v_cvt_pk_bf16_f32 v91, v100, v101
	v_cvt_pk_bf16_f32 v92, v92, v93
	v_cvt_pk_bf16_f32 v93, v102, v103
	global_store_dwordx4 v[120:121], v[90:93], off offset:64 sc1
	s_cbranch_scc1 .LBB0_448
	s_cmp_lg_u32 s11, 5
	s_cselect_b64 s[2:3], -1, 0
	s_cbranch_execz .LBB0_449
	s_branch .LBB0_450

; __device__ __forceinline__ unsigned cvt_pk_bf16(float lo, float hi) { unsigned r; asm volatile("v_cvt_pk_bf16_f32 %0, %1, %2" : "=v"(r) : "v"(lo), "v"(hi)); return r; }
;     __device__ __forceinline__ void operator()(const f32x4 (&acc)[2][2][4][2], const Unit& u, int wr, int wc, int fr, int fq) const {
;     ...
;                 bf16_t* rowp = U + (size_t)row * 3072 + col0;
; #pragma unroll
;                 for (int bj = 0; bj < 2; ++bj) {
;                     const f32x4 v0 = v[bj][0] * gv[bj][0] * sc, v1 = v[bj][1] * gv[bj][1] * sc;
;                     u32x4 w; w.x = cvt_pk_bf16(v0[0], v0[1]); w.y = cvt_pk_bf16(v0[2], v0[3]); w.z = cvt_pk_bf16(v1[0], v1[1]); w.w = cvt_pk_bf16(v1[2], v1[3]);
;                     *(u32x4*)(rowp + 32 * bj) = w;
.LBB0_452:
	v_or_b32_e32 v91, 48, v177
	v_mov_b64_e32 v[92:93], s[84:85]
	v_mad_i64_i32 v[92:93], s[2:3], v91, s87, v[92:93]
	v_pk_mul_f32 v[80:81], v[204:205], v[80:81]
	v_pk_mul_f32 v[78:79], v[202:203], v[78:79]
	v_pk_mul_f32 v[76:77], v[208:209], v[76:77]
	v_pk_mul_f32 v[74:75], v[206:207], v[74:75]
	v_lshl_add_u64 v[92:93], v[138:139], 1, v[92:93]
	v_pk_mul_f32 v[80:81], v[80:81], v[90:91] op_sel_hi:[1,0]
	v_pk_mul_f32 v[78:79], v[78:79], v[90:91] op_sel_hi:[1,0]
	v_pk_mul_f32 v[98:99], v[76:77], v[90:91] op_sel_hi:[1,0]
	v_pk_mul_f32 v[76:77], v[74:75], v[90:91] op_sel_hi:[1,0]
	v_cvt_pk_bf16_f32 v74, v78, v79
	v_cvt_pk_bf16_f32 v75, v80, v81
	v_pk_mul_f32 v[68:69], v[216:217], v[68:69]
	v_pk_mul_f32 v[66:67], v[214:215], v[66:67]
	v_cvt_pk_bf16_f32 v76, v76, v77
	v_cvt_pk_bf16_f32 v77, v98, v99
	global_store_dwordx4 v[92:93], v[74:77], off sc1
	v_pk_mul_f32 v[72:73], v[212:213], v[72:73]
	v_pk_mul_f32 v[70:71], v[210:211], v[70:71]
	v_pk_mul_f32 v[74:75], v[68:69], v[90:91] op_sel_hi:[1,0]
	v_pk_mul_f32 v[68:69], v[66:67], v[90:91] op_sel_hi:[1,0]
	s_cmp_lt_i32 s11, 5
	v_pk_mul_f32 v[72:73], v[72:73], v[90:91] op_sel_hi:[1,0]
	v_pk_mul_f32 v[70:71], v[70:71], v[90:91] op_sel_hi:[1,0]
	s_nop 0
	v_cvt_pk_bf16_f32 v66, v70, v71
	v_cvt_pk_bf16_f32 v67, v72, v73
	v_cvt_pk_bf16_f32 v68, v68, v69
	v_cvt_pk_bf16_f32 v69, v74, v75
	global_store_dwordx4 v[92:93], v[66:69], off offset:64 sc1
	s_cbranch_scc1 .LBB0_454
	s_cmp_lg_u32 s11, 5
	s_cselect_b64 s[2:3], -1, 0
	s_cbranch_execz .LBB0_455
	s_branch .LBB0_456

; __device__ __forceinline__ unsigned cvt_pk_bf16(float lo, float hi) { unsigned r; asm volatile("v_cvt_pk_bf16_f32 %0, %1, %2" : "=v"(r) : "v"(lo), "v"(hi)); return r; }
;     __device__ __forceinline__ void operator()(const f32x4 (&acc)[2][2][4][2], const Unit& u, int wr, int wc, int fr, int fq) const {
;     ...
;                 bf16_t* rowp = U + (size_t)row * 3072 + col0;
; #pragma unroll
;                 for (int bj = 0; bj < 2; ++bj) {
;                     const f32x4 v0 = v[bj][0] * gv[bj][0] * sc, v1 = v[bj][1] * gv[bj][1] * sc;
;                     u32x4 w; w.x = cvt_pk_bf16(v0[0], v0[1]); w.y = cvt_pk_bf16(v0[2], v0[3]); w.z = cvt_pk_bf16(v1[0], v1[1]); w.w = cvt_pk_bf16(v1[2], v1[3]);
;                     *(u32x4*)(rowp + 32 * bj) = w;
.LBB0_458:
	v_add_u32_e32 v67, 0x80, v177
	v_mov_b64_e32 v[68:69], s[84:85]
	v_mad_i64_i32 v[68:69], s[2:3], v67, s87, v[68:69]
	v_pk_mul_f32 v[64:65], v[204:205], v[64:65]
	v_pk_mul_f32 v[62:63], v[202:203], v[62:63]
	v_pk_mul_f32 v[60:61], v[208:209], v[60:61]
	v_pk_mul_f32 v[58:59], v[206:207], v[58:59]
	v_lshl_add_u64 v[68:69], v[138:139], 1, v[68:69]
	v_pk_mul_f32 v[64:65], v[64:65], v[66:67] op_sel_hi:[1,0]
	v_pk_mul_f32 v[62:63], v[62:63], v[66:67] op_sel_hi:[1,0]
	v_pk_mul_f32 v[70:71], v[60:61], v[66:67] op_sel_hi:[1,0]
	v_pk_mul_f32 v[60:61], v[58:59], v[66:67] op_sel_hi:[1,0]
	v_cvt_pk_bf16_f32 v58, v62, v63
	v_cvt_pk_bf16_f32 v59, v64, v65
	v_pk_mul_f32 v[52:53], v[216:217], v[52:53]
	v_pk_mul_f32 v[50:51], v[214:215], v[50:51]
	v_cvt_pk_bf16_f32 v60, v60, v61
	v_cvt_pk_bf16_f32 v61, v70, v71
	global_store_dwordx4 v[68:69], v[58:61], off sc1
	v_pk_mul_f32 v[56:57], v[212:213], v[56:57]
	v_pk_mul_f32 v[54:55], v[210:211], v[54:55]
	v_pk_mul_f32 v[58:59], v[52:53], v[66:67] op_sel_hi:[1,0]
	v_pk_mul_f32 v[52:53], v[50:51], v[66:67] op_sel_hi:[1,0]
	s_cmp_lt_i32 s11, 5
	v_pk_mul_f32 v[56:57], v[56:57], v[66:67] op_sel_hi:[1,0]
	v_pk_mul_f32 v[54:55], v[54:55], v[66:67] op_sel_hi:[1,0]
	s_nop 0
	v_cvt_pk_bf16_f32 v50, v54, v55
	v_cvt_pk_bf16_f32 v51, v56, v57
	v_cvt_pk_bf16_f32 v52, v52, v53
	v_cvt_pk_bf16_f32 v53, v58, v59
	global_store_dwordx4 v[68:69], v[50:53], off offset:64 sc1
	s_cbranch_scc1 .LBB0_460
	s_cmp_lg_u32 s11, 5
	s_cselect_b64 s[2:3], -1, 0
	s_cbranch_execz .LBB0_461
	s_branch .LBB0_462

; __device__ __forceinline__ unsigned cvt_pk_bf16(float lo, float hi) { unsigned r; asm volatile("v_cvt_pk_bf16_f32 %0, %1, %2" : "=v"(r) : "v"(lo), "v"(hi)); return r; }
;     __device__ __forceinline__ void operator()(const f32x4 (&acc)[2][2][4][2], const Unit& u, int wr, int wc, int fr, int fq) const {
;     ...
;                 bf16_t* rowp = U + (size_t)row * 3072 + col0;
; #pragma unroll
;                 for (int bj = 0; bj < 2; ++bj) {
;                     const f32x4 v0 = v[bj][0] * gv[bj][0] * sc, v1 = v[bj][1] * gv[bj][1] * sc;
;                     u32x4 w; w.x = cvt_pk_bf16(v0[0], v0[1]); w.y = cvt_pk_bf16(v0[2], v0[3]); w.z = cvt_pk_bf16(v1[0], v1[1]); w.w = cvt_pk_bf16(v1[2], v1[3]);
;                     *(u32x4*)(rowp + 32 * bj) = w;
.LBB0_464:
	v_add_u32_e32 v51, 0x90, v177
	v_mov_b64_e32 v[52:53], s[84:85]
	v_mad_i64_i32 v[52:53], s[2:3], v51, s87, v[52:53]
	v_pk_mul_f32 v[48:49], v[204:205], v[48:49]
	v_pk_mul_f32 v[46:47], v[202:203], v[46:47]
	v_pk_mul_f32 v[44:45], v[208:209], v[44:45]
	v_pk_mul_f32 v[42:43], v[206:207], v[42:43]
	v_lshl_add_u64 v[52:53], v[138:139], 1, v[52:53]
	v_pk_mul_f32 v[48:49], v[48:49], v[50:51] op_sel_hi:[1,0]
	v_pk_mul_f32 v[46:47], v[46:47], v[50:51] op_sel_hi:[1,0]
	v_pk_mul_f32 v[54:55], v[44:45], v[50:51] op_sel_hi:[1,0]
	v_pk_mul_f32 v[44:45], v[42:43], v[50:51] op_sel_hi:[1,0]
	v_cvt_pk_bf16_f32 v42, v46, v47
	v_cvt_pk_bf16_f32 v43, v48, v49
	v_pk_mul_f32 v[36:37], v[216:217], v[36:37]
	v_pk_mul_f32 v[34:35], v[214:215], v[34:35]
	v_cvt_pk_bf16_f32 v44, v44, v45
	v_cvt_pk_bf16_f32 v45, v54, v55
	global_store_dwordx4 v[52:53], v[42:45], off sc1
	v_pk_mul_f32 v[40:41], v[212:213], v[40:41]
	v_pk_mul_f32 v[38:39], v[210:211], v[38:39]
	v_pk_mul_f32 v[42:43], v[36:37], v[50:51] op_sel_hi:[1,0]
	v_pk_mul_f32 v[36:37], v[34:35], v[50:51] op_sel_hi:[1,0]
	s_cmp_lt_i32 s11, 5
	v_pk_mul_f32 v[40:41], v[40:41], v[50:51] op_sel_hi:[1,0]
	v_pk_mul_f32 v[38:39], v[38:39], v[50:51] op_sel_hi:[1,0]
	s_nop 0
	v_cvt_pk_bf16_f32 v34, v38, v39
	v_cvt_pk_bf16_f32 v35, v40, v41
	v_cvt_pk_bf16_f32 v36, v36, v37
	v_cvt_pk_bf16_f32 v37, v42, v43
	global_store_dwordx4 v[52:53], v[34:37], off offset:64 sc1
	s_cbranch_scc1 .LBB0_466
	s_cmp_lg_u32 s11, 5
	s_cselect_b64 s[2:3], -1, 0
	s_cbranch_execz .LBB0_467
	s_branch .LBB0_468

; __device__ __forceinline__ unsigned cvt_pk_bf16(float lo, float hi) { unsigned r; asm volatile("v_cvt_pk_bf16_f32 %0, %1, %2" : "=v"(r) : "v"(lo), "v"(hi)); return r; }
;     __device__ __forceinline__ void operator()(const f32x4 (&acc)[2][2][4][2], const Unit& u, int wr, int wc, int fr, int fq) const {
;     ...
;                 bf16_t* rowp = U + (size_t)row * 3072 + col0;
; #pragma unroll
;                 for (int bj = 0; bj < 2; ++bj) {
;                     const f32x4 v0 = v[bj][0] * gv[bj][0] * sc, v1 = v[bj][1] * gv[bj][1] * sc;
;                     u32x4 w; w.x = cvt_pk_bf16(v0[0], v0[1]); w.y = cvt_pk_bf16(v0[2], v0[3]); w.z = cvt_pk_bf16(v1[0], v1[1]); w.w = cvt_pk_bf16(v1[2], v1[3]);
;                     *(u32x4*)(rowp + 32 * bj) = w;
.LBB0_470:
	v_add_u32_e32 v35, 0xa0, v177
	v_mov_b64_e32 v[36:37], s[84:85]
	v_mad_i64_i32 v[36:37], s[2:3], v35, s87, v[36:37]
	v_pk_mul_f32 v[32:33], v[204:205], v[32:33]
	v_pk_mul_f32 v[30:31], v[202:203], v[30:31]
	v_pk_mul_f32 v[28:29], v[208:209], v[28:29]
	v_pk_mul_f32 v[26:27], v[206:207], v[26:27]
	v_lshl_add_u64 v[36:37], v[138:139], 1, v[36:37]
	v_pk_mul_f32 v[32:33], v[32:33], v[34:35] op_sel_hi:[1,0]
	v_pk_mul_f32 v[30:31], v[30:31], v[34:35] op_sel_hi:[1,0]
	v_pk_mul_f32 v[38:39], v[28:29], v[34:35] op_sel_hi:[1,0]
	v_pk_mul_f32 v[28:29], v[26:27], v[34:35] op_sel_hi:[1,0]
	v_cvt_pk_bf16_f32 v26, v30, v31
	v_cvt_pk_bf16_f32 v27, v32, v33
	v_pk_mul_f32 v[20:21], v[216:217], v[20:21]
	v_pk_mul_f32 v[18:19], v[214:215], v[18:19]
	v_cvt_pk_bf16_f32 v28, v28, v29
	v_cvt_pk_bf16_f32 v29, v38, v39
	global_store_dwordx4 v[36:37], v[26:29], off sc1
	v_pk_mul_f32 v[24:25], v[212:213], v[24:25]
	v_pk_mul_f32 v[22:23], v[210:211], v[22:23]
	v_pk_mul_f32 v[26:27], v[20:21], v[34:35] op_sel_hi:[1,0]
	v_pk_mul_f32 v[20:21], v[18:19], v[34:35] op_sel_hi:[1,0]
	s_cmp_lt_i32 s11, 5
	v_pk_mul_f32 v[24:25], v[24:25], v[34:35] op_sel_hi:[1,0]
	v_pk_mul_f32 v[22:23], v[22:23], v[34:35] op_sel_hi:[1,0]
	s_nop 0
	v_cvt_pk_bf16_f32 v18, v22, v23
	v_cvt_pk_bf16_f32 v19, v24, v25
	v_cvt_pk_bf16_f32 v20, v20, v21
	v_cvt_pk_bf16_f32 v21, v26, v27
	global_store_dwordx4 v[36:37], v[18:21], off offset:64 sc1
	s_cbranch_scc1 .LBB0_472
	s_cmp_lg_u32 s11, 5
	s_cselect_b64 s[2:3], -1, 0
	s_cbranch_execz .LBB0_473
	s_branch .LBB0_474

; __device__ __forceinline__ unsigned cvt_pk_bf16(float lo, float hi) { unsigned r; asm volatile("v_cvt_pk_bf16_f32 %0, %1, %2" : "=v"(r) : "v"(lo), "v"(hi)); return r; }
;     __device__ __forceinline__ void operator()(const f32x4 (&acc)[2][2][4][2], const Unit& u, int wr, int wc, int fr, int fq) const {
;     ...
;                 bf16_t* rowp = U + (size_t)row * 3072 + col0;
; #pragma unroll
;                 for (int bj = 0; bj < 2; ++bj) {
;                     const f32x4 v0 = v[bj][0] * gv[bj][0] * sc, v1 = v[bj][1] * gv[bj][1] * sc;
;                     u32x4 w; w.x = cvt_pk_bf16(v0[0], v0[1]); w.y = cvt_pk_bf16(v0[2], v0[3]); w.z = cvt_pk_bf16(v1[0], v1[1]); w.w = cvt_pk_bf16(v1[2], v1[3]);
;                     *(u32x4*)(rowp + 32 * bj) = w;
.LBB0_476:
	v_add_u32_e32 v19, 0xb0, v177
	v_mov_b64_e32 v[20:21], s[84:85]
	v_mad_i64_i32 v[20:21], s[2:3], v19, s87, v[20:21]
	v_pk_mul_f32 v[16:17], v[204:205], v[16:17]
	v_pk_mul_f32 v[14:15], v[202:203], v[14:15]
	v_pk_mul_f32 v[12:13], v[208:209], v[12:13]
	v_pk_mul_f32 v[10:11], v[206:207], v[10:11]
	v_lshl_add_u64 v[20:21], v[138:139], 1, v[20:21]
	v_pk_mul_f32 v[16:17], v[16:17], v[18:19] op_sel_hi:[1,0]
	v_pk_mul_f32 v[14:15], v[14:15], v[18:19] op_sel_hi:[1,0]
	v_pk_mul_f32 v[22:23], v[12:13], v[18:19] op_sel_hi:[1,0]
	v_pk_mul_f32 v[12:13], v[10:11], v[18:19] op_sel_hi:[1,0]
	v_cvt_pk_bf16_f32 v10, v14, v15
	v_cvt_pk_bf16_f32 v11, v16, v17
	v_pk_mul_f32 v[4:5], v[216:217], v[4:5]
	v_pk_mul_f32 v[2:3], v[214:215], v[2:3]
	v_cvt_pk_bf16_f32 v12, v12, v13
	v_cvt_pk_bf16_f32 v13, v22, v23
	global_store_dwordx4 v[20:21], v[10:13], off sc1
	v_pk_mul_f32 v[8:9], v[212:213], v[8:9]
	v_pk_mul_f32 v[6:7], v[210:211], v[6:7]
	v_pk_mul_f32 v[10:11], v[4:5], v[18:19] op_sel_hi:[1,0]
	v_pk_mul_f32 v[4:5], v[2:3], v[18:19] op_sel_hi:[1,0]
	s_andn2_b64 vcc, exec, s[0:1]
	s_mov_b64 s[0:1], -1
	v_pk_mul_f32 v[8:9], v[8:9], v[18:19] op_sel_hi:[1,0]
	v_pk_mul_f32 v[6:7], v[6:7], v[18:19] op_sel_hi:[1,0]
	s_nop 0
	v_cvt_pk_bf16_f32 v2, v6, v7
	v_cvt_pk_bf16_f32 v3, v8, v9
	v_cvt_pk_bf16_f32 v4, v4, v5
	v_cvt_pk_bf16_f32 v5, v10, v11
	global_store_dwordx4 v[20:21], v[2:5], off offset:64 sc1
	s_cbranch_vccnz .LBB0_394
	v_readlane_b32 s0, v253, 36
	v_readlane_b32 s1, v253, 37
	s_andn2_b64 vcc, exec, s[0:1]
	s_cbranch_vccnz .LBB0_393
	s_barrier
	s_branch .LBB0_393
